# pooling mixer: hand-written fast path with batched window-row loads (64 serialized load->wait round trips per wave removed); boundary blocks keep the original code
# speedup vs baseline: 1.0113x; 1.0113x over previous
; __device__ __forceinline__ int otid() { int t = threadIdx.x; asm volatile("" : "+v"(t)); return t; }
; __device__ __forceinline__ void unpack8(const u32x4 v, float* a) { a[0] = bflo(v.x); a[1] = bfhi(v.x); a[2] = bflo(v.y); a[3] = bfhi(v.y); a[4] = bflo(v.z); a[5] = bfhi(v.z); a[6] = bflo(v.w); a[7] = bfhi(v.w); }
; #define PIN(i) karg_ptr(8 * (i))
; __device__ __forceinline__ void pool_block(const bf16_t* Z, bf16_t* A2, int row0, int lane) {
;     int sb, S; if (row0 < 8192) { sb = 0; S = 8192; } else if (row0 < 16384) { sb = 8192; S = 8192; } else { sb = 16384; S = 16384; }
;     const int t0 = row0 - sb, g = lane >> 4, hw = 1 << g;
;     const bf16_t* base = Z + (size_t)sb * NZ + 1536 + lane * 8;
;     float sum[8], tmp[8];
; #pragma unroll
;     for (int j = 0; j < 8; ++j) sum[j] = 0.f;
; #pragma unroll
;     for (int j = 0; j < 16; ++j) { const int r = t0 - hw + j;
;         if (j < 2 * hw && r >= 0 && r < S) { unpack8(*(const u32x4*)(base + (size_t)r * NZ), tmp);
; #pragma unroll
;             for (int e = 0; e < 8; ++e) sum[e] += tmp[e]; } }
; __global__ void __launch_bounds__(512, 2) fwd_megakernel(Params P) {
;     ...
;             { const int lane = otid() & 63; const float* lq = PIN(I_LAMQ) + l * 128; const float* lk = PIN(I_LAMK) + l * 128;
;               const float a = wave_sum(lq[lane] * lk[lane]), b = wave_sum(lq[64 + lane] * lk[64 + lane]);
;               lam = expf(a) - expf(b) + (0.8f - 0.6f * expf(-0.3f * (float)l)); }
;             { const int lane_ = otid() & 63, gwv = bx * 8 + (otid() >> 6);
;               for (int tb = gwv; tb < MTOK / 16; tb += G * 8) att::pool_block(Zb, A2, tb * 16, lane_); }
.LBB0_225:
	s_andn2_b64 vcc, exec, s[6:7]
	s_cbranch_vccnz .LBB0_402
	v_mov_b32_e32 v2, v0
	s_mov_b64 s[6:7], s[0:1]
	s_load_dwordx2 s[6:7], s[6:7], 0x30
	s_mov_b64 s[8:9], s[0:1]
	s_load_dwordx2 s[8:9], s[8:9], 0x38
	v_readlane_b32 s10, v255, 49
	v_readlane_b32 s11, v255, 50
	s_lshl_b32 s48, s10, 7
	s_lshl_b64 s[10:11], s[48:49], 2
	s_waitcnt lgkmcnt(0)
	s_add_u32 s6, s6, s10
	v_and_b32_e32 v2, 63, v2
	s_addc_u32 s7, s7, s11
	s_add_u32 s8, s8, s10
	v_lshlrev_b32_e32 v2, 2, v2
	s_addc_u32 s9, s9, s11
	global_load_dword v3, v2, s[6:7]
	global_load_dword v4, v2, s[8:9]
	global_load_dword v5, v2, s[8:9] offset:256
	global_load_dword v6, v2, s[6:7] offset:256
	v_and_b32_e32 v7, 64, v246
	v_xor_b32_e32 v8, 1, v246
	v_add_u32_e32 v7, 64, v7
	v_cmp_lt_i32_e32 vcc, v8, v7
	v_xor_b32_e32 v9, 2, v246
	v_xor_b32_e32 v10, 4, v246
	v_cndmask_b32_e32 v8, v246, v8, vcc
	v_lshlrev_b32_e32 v152, 2, v8
	v_cmp_lt_i32_e32 vcc, v9, v7
	v_xor_b32_e32 v11, 8, v246
	v_xor_b32_e32 v12, 16, v246
	v_cndmask_b32_e32 v9, v246, v9, vcc
	v_lshlrev_b32_e32 v153, 2, v9
	v_cmp_lt_i32_e32 vcc, v10, v7
	v_xor_b32_e32 v13, 32, v246
	v_mov_b32_e32 v2, v0
	v_readlane_b32 s6, v255, 4
	s_waitcnt vmcnt(0)
	v_mul_f32_e32 v8, v3, v4
	ds_bpermute_b32 v8, v152, v8
	s_waitcnt vmcnt(0)
	v_mul_f32_e32 v14, v6, v5
	ds_bpermute_b32 v14, v152, v14
	s_waitcnt lgkmcnt(1)
	v_fmac_f32_e32 v8, v3, v4
	ds_bpermute_b32 v3, v153, v8
	s_waitcnt lgkmcnt(1)
	v_fmac_f32_e32 v14, v6, v5
	ds_bpermute_b32 v4, v153, v14
	v_cndmask_b32_e32 v5, v246, v10, vcc
	v_lshlrev_b32_e32 v154, 2, v5
	s_waitcnt lgkmcnt(1)
	v_add_f32_e32 v3, v8, v3
	ds_bpermute_b32 v5, v154, v3
	s_waitcnt lgkmcnt(1)
	v_add_f32_e32 v4, v14, v4
	ds_bpermute_b32 v6, v154, v4
	v_cmp_lt_i32_e32 vcc, v11, v7
	s_waitcnt lgkmcnt(1)
	v_add_f32_e32 v3, v3, v5
	v_cndmask_b32_e32 v8, v246, v11, vcc
	v_lshlrev_b32_e32 v155, 2, v8
	s_waitcnt lgkmcnt(0)
	v_add_f32_e32 v4, v4, v6
	ds_bpermute_b32 v5, v155, v3
	ds_bpermute_b32 v6, v155, v4
	v_cmp_lt_i32_e32 vcc, v12, v7
	s_waitcnt lgkmcnt(1)
	v_add_f32_e32 v3, v3, v5
	v_cndmask_b32_e32 v8, v246, v12, vcc
	v_lshlrev_b32_e32 v156, 2, v8
	s_waitcnt lgkmcnt(0)
	v_add_f32_e32 v4, v4, v6
	ds_bpermute_b32 v5, v156, v3
	ds_bpermute_b32 v6, v156, v4
	v_cmp_lt_i32_e32 vcc, v13, v7
	s_waitcnt lgkmcnt(1)
	v_add_f32_e32 v3, v3, v5
	v_cndmask_b32_e32 v7, v246, v13, vcc
	v_lshlrev_b32_e32 v157, 2, v7
	s_waitcnt lgkmcnt(0)
	v_add_f32_e32 v26, v4, v6
	ds_bpermute_b32 v27, v157, v3
	ds_bpermute_b32 v28, v157, v26
	v_mov_b32_e32 v4, v0
	s_nop 0
	v_ashrrev_i32_e32 v4, 6, v4
	v_add_u32_e32 v29, s6, v4
	s_movk_i32 s6, 0x800
	v_cmp_gt_i32_e32 vcc, s6, v29
	s_and_saveexec_b64 s[14:15], vcc
	s_cbranch_execz .LBB0_279
	v_lshrrev_b32_e32 v144, 6, v0
	v_readlane_b32 s10, v255, 4
	v_readfirstlane_b32 s11, v144
	s_add_i32 s10, s10, s11
	s_lshl_b32 s10, s10, 4
	s_and_b32 s11, s10, 0x1fff
	s_cmp_eq_u32 s11, 0
	s_cbranch_scc1 .Lpool_slow
	s_add_i32 s11, s10, 16
	s_and_b32 s11, s11, 0x1fff
	s_cmp_eq_u32 s11, 0
	s_cbranch_scc1 .Lpool_slow
	s_load_dwordx2 s[6:7], s[0:1], 0x98
	s_load_dwordx2 s[8:9], s[0:1], 0x90
	v_and_b32_e32 v144, 63, v0
	v_lshrrev_b32_e32 v141, 4, v144
	s_lshl_b32 s11, s10, 12
	s_add_u32 s11, s11, 0x7800c00
	v_lshl_add_u32 v140, v144, 4, s11
	v_mov_b32_e32 v142, 0x1000
	v_lshlrev_b32_e32 v142, v141, v142
	v_lshlrev_b32_e32 v24, 23, v141
	v_sub_u32_e32 v24, 0x3f000000, v24
	v_add_u32_e32 v141, v140, v142
	v_sub_u32_e32 v142, v140, v142
	s_lshl_b32 s11, s10, 11
	s_add_u32 s11, s11, 1024
	v_lshl_add_u32 v143, v144, 4, s11
	v_mov_b32_e32 v6, 0
	v_mov_b32_e32 v7, 0
	v_mov_b32_e32 v8, 0
	v_mov_b32_e32 v9, 0
	v_mov_b32_e32 v10, 0
	v_mov_b32_e32 v11, 0
	v_mov_b32_e32 v12, 0
	v_mov_b32_e32 v13, 0
	s_waitcnt lgkmcnt(0)
	global_load_dwordx4 v[36:39], v140, s[6:7]
	global_load_dwordx4 v[68:71], v141, s[6:7]
	global_load_dwordx4 v[100:103], v142, s[6:7]
	v_add_u32_e32 v140, 0x1000, v140
	v_add_u32_e32 v141, 0x1000, v141
	v_add_u32_e32 v142, 0x1000, v142
	global_load_dwordx4 v[40:43], v140, s[6:7]
	global_load_dwordx4 v[72:75], v141, s[6:7]
	global_load_dwordx4 v[104:107], v142, s[6:7]
	v_add_u32_e32 v140, 0x1000, v140
	v_add_u32_e32 v141, 0x1000, v141
	v_add_u32_e32 v142, 0x1000, v142
	global_load_dwordx4 v[44:47], v140, s[6:7]
	global_load_dwordx4 v[76:79], v141, s[6:7]
	global_load_dwordx4 v[108:111], v142, s[6:7]
	v_add_u32_e32 v140, 0x1000, v140
	v_add_u32_e32 v141, 0x1000, v141
	v_add_u32_e32 v142, 0x1000, v142
	global_load_dwordx4 v[48:51], v140, s[6:7]
	global_load_dwordx4 v[80:83], v141, s[6:7]
	global_load_dwordx4 v[112:115], v142, s[6:7]
	v_add_u32_e32 v140, 0x1000, v140
	v_add_u32_e32 v141, 0x1000, v141
	v_add_u32_e32 v142, 0x1000, v142
	global_load_dwordx4 v[52:55], v140, s[6:7]
	global_load_dwordx4 v[84:87], v141, s[6:7]
	global_load_dwordx4 v[116:119], v142, s[6:7]
	v_add_u32_e32 v140, 0x1000, v140
	v_add_u32_e32 v141, 0x1000, v141
	v_add_u32_e32 v142, 0x1000, v142
	global_load_dwordx4 v[56:59], v140, s[6:7]
	global_load_dwordx4 v[88:91], v141, s[6:7]
	global_load_dwordx4 v[120:123], v142, s[6:7]
	v_add_u32_e32 v140, 0x1000, v140
	v_add_u32_e32 v141, 0x1000, v141
	v_add_u32_e32 v142, 0x1000, v142
	global_load_dwordx4 v[60:63], v140, s[6:7]
	global_load_dwordx4 v[92:95], v141, s[6:7]
	global_load_dwordx4 v[124:127], v142, s[6:7]
	v_add_u32_e32 v140, 0x1000, v140
	v_add_u32_e32 v141, 0x1000, v141
	v_add_u32_e32 v142, 0x1000, v142
	global_load_dwordx4 v[64:67], v140, s[6:7]
	global_load_dwordx4 v[96:99], v141, s[6:7]
	global_load_dwordx4 v[128:131], v142, s[6:7]
	v_add_u32_e32 v140, 0x1000, v140
	v_add_u32_e32 v141, 0x1000, v141
	v_add_u32_e32 v142, 0x1000, v142
	s_waitcnt vmcnt(0)
; __device__ __forceinline__ void unpack8(const u32x4 v, float* a) { a[0] = bflo(v.x); a[1] = bfhi(v.x); a[2] = bflo(v.y); a[3] = bfhi(v.y); a[4] = bflo(v.z); a[5] = bfhi(v.z); a[6] = bflo(v.w); a[7] = bfhi(v.w); }
; __device__ __forceinline__ void pool_block(const bf16_t* Z, bf16_t* A2, int row0, int lane) {
;     ...
;     for (int j = 0; j < 16; ++j) { const int r = t0 - hw + j;
;         if (j < 2 * hw && r >= 0 && r < S) { unpack8(*(const u32x4*)(base + (size_t)r * NZ), tmp);
; #pragma unroll
;             for (int e = 0; e < 8; ++e) sum[e] += tmp[e]; } }
	s_mov_b64 exec, -1
	v_lshlrev_b32_e32 v14, 16, v100
	v_and_b32_e32 v15, 0xffff0000, v100
	v_lshlrev_b32_e32 v16, 16, v101
	v_and_b32_e32 v17, 0xffff0000, v101
	v_lshlrev_b32_e32 v18, 16, v102
	v_and_b32_e32 v19, 0xffff0000, v102
	v_lshlrev_b32_e32 v20, 16, v103
	v_and_b32_e32 v21, 0xffff0000, v103
	v_pk_add_f32 v[6:7], v[6:7], v[14:15]
	v_pk_add_f32 v[8:9], v[8:9], v[16:17]
	v_pk_add_f32 v[10:11], v[10:11], v[18:19]
	v_pk_add_f32 v[12:13], v[12:13], v[20:21]
	s_bfm_b64 exec, 48, 16
	v_lshlrev_b32_e32 v14, 16, v104
	v_and_b32_e32 v15, 0xffff0000, v104
	v_lshlrev_b32_e32 v16, 16, v105
	v_and_b32_e32 v17, 0xffff0000, v105
	v_lshlrev_b32_e32 v18, 16, v106
	v_and_b32_e32 v19, 0xffff0000, v106
	v_lshlrev_b32_e32 v20, 16, v107
	v_and_b32_e32 v21, 0xffff0000, v107
	v_pk_add_f32 v[6:7], v[6:7], v[14:15]
	v_pk_add_f32 v[8:9], v[8:9], v[16:17]
	v_pk_add_f32 v[10:11], v[10:11], v[18:19]
	v_pk_add_f32 v[12:13], v[12:13], v[20:21]
	s_bfm_b64 exec, 32, 32
	v_lshlrev_b32_e32 v14, 16, v108
	v_and_b32_e32 v15, 0xffff0000, v108
	v_lshlrev_b32_e32 v16, 16, v109
	v_and_b32_e32 v17, 0xffff0000, v109
	v_lshlrev_b32_e32 v18, 16, v110
	v_and_b32_e32 v19, 0xffff0000, v110
	v_lshlrev_b32_e32 v20, 16, v111
	v_and_b32_e32 v21, 0xffff0000, v111
	v_pk_add_f32 v[6:7], v[6:7], v[14:15]
	v_pk_add_f32 v[8:9], v[8:9], v[16:17]
	v_pk_add_f32 v[10:11], v[10:11], v[18:19]
	v_pk_add_f32 v[12:13], v[12:13], v[20:21]
	v_lshlrev_b32_e32 v14, 16, v112
	v_and_b32_e32 v15, 0xffff0000, v112
	v_lshlrev_b32_e32 v16, 16, v113
	v_and_b32_e32 v17, 0xffff0000, v113
	v_lshlrev_b32_e32 v18, 16, v114
	v_and_b32_e32 v19, 0xffff0000, v114
	v_lshlrev_b32_e32 v20, 16, v115
	v_and_b32_e32 v21, 0xffff0000, v115
	v_pk_add_f32 v[6:7], v[6:7], v[14:15]
	v_pk_add_f32 v[8:9], v[8:9], v[16:17]
	v_pk_add_f32 v[10:11], v[10:11], v[18:19]
	v_pk_add_f32 v[12:13], v[12:13], v[20:21]
	s_bfm_b64 exec, 16, 48
	v_lshlrev_b32_e32 v14, 16, v116
	v_and_b32_e32 v15, 0xffff0000, v116
	v_lshlrev_b32_e32 v16, 16, v117
	v_and_b32_e32 v17, 0xffff0000, v117
	v_lshlrev_b32_e32 v18, 16, v118
	v_and_b32_e32 v19, 0xffff0000, v118
	v_lshlrev_b32_e32 v20, 16, v119
	v_and_b32_e32 v21, 0xffff0000, v119
	v_pk_add_f32 v[6:7], v[6:7], v[14:15]
	v_pk_add_f32 v[8:9], v[8:9], v[16:17]
	v_pk_add_f32 v[10:11], v[10:11], v[18:19]
	v_pk_add_f32 v[12:13], v[12:13], v[20:21]
	v_lshlrev_b32_e32 v14, 16, v120
	v_and_b32_e32 v15, 0xffff0000, v120
	v_lshlrev_b32_e32 v16, 16, v121
	v_and_b32_e32 v17, 0xffff0000, v121
	v_lshlrev_b32_e32 v18, 16, v122
	v_and_b32_e32 v19, 0xffff0000, v122
	v_lshlrev_b32_e32 v20, 16, v123
	v_and_b32_e32 v21, 0xffff0000, v123
	v_pk_add_f32 v[6:7], v[6:7], v[14:15]
	v_pk_add_f32 v[8:9], v[8:9], v[16:17]
	v_pk_add_f32 v[10:11], v[10:11], v[18:19]
	v_pk_add_f32 v[12:13], v[12:13], v[20:21]
	v_lshlrev_b32_e32 v14, 16, v124
	v_and_b32_e32 v15, 0xffff0000, v124
	v_lshlrev_b32_e32 v16, 16, v125
	v_and_b32_e32 v17, 0xffff0000, v125
	v_lshlrev_b32_e32 v18, 16, v126
	v_and_b32_e32 v19, 0xffff0000, v126
	v_lshlrev_b32_e32 v20, 16, v127
	v_and_b32_e32 v21, 0xffff0000, v127
	v_pk_add_f32 v[6:7], v[6:7], v[14:15]
	v_pk_add_f32 v[8:9], v[8:9], v[16:17]
	v_pk_add_f32 v[10:11], v[10:11], v[18:19]
	v_pk_add_f32 v[12:13], v[12:13], v[20:21]
	v_lshlrev_b32_e32 v14, 16, v128
	v_and_b32_e32 v15, 0xffff0000, v128
	v_lshlrev_b32_e32 v16, 16, v129
	v_and_b32_e32 v17, 0xffff0000, v129
	v_lshlrev_b32_e32 v18, 16, v130
	v_and_b32_e32 v19, 0xffff0000, v130
	v_lshlrev_b32_e32 v20, 16, v131
	v_and_b32_e32 v21, 0xffff0000, v131
	v_pk_add_f32 v[6:7], v[6:7], v[14:15]
	v_pk_add_f32 v[8:9], v[8:9], v[16:17]
	v_pk_add_f32 v[10:11], v[10:11], v[18:19]
	v_pk_add_f32 v[12:13], v[12:13], v[20:21]
	s_mov_b64 exec, -1
	v_lshlrev_b32_e32 v14, 16, v36
	v_and_b32_e32 v15, 0xffff0000, v36
	v_lshlrev_b32_e32 v16, 16, v37
	v_and_b32_e32 v17, 0xffff0000, v37
	v_lshlrev_b32_e32 v18, 16, v38
	v_and_b32_e32 v19, 0xffff0000, v38
	v_lshlrev_b32_e32 v20, 16, v39
	v_and_b32_e32 v21, 0xffff0000, v39
	v_pk_add_f32 v[6:7], v[6:7], v[14:15]
	v_pk_add_f32 v[8:9], v[8:9], v[16:17]
	v_pk_add_f32 v[10:11], v[10:11], v[18:19]
	v_pk_add_f32 v[12:13], v[12:13], v[20:21]
	s_bfm_b64 exec, 48, 16
	v_lshlrev_b32_e32 v14, 16, v40
	v_and_b32_e32 v15, 0xffff0000, v40
	v_lshlrev_b32_e32 v16, 16, v41
	v_and_b32_e32 v17, 0xffff0000, v41
	v_lshlrev_b32_e32 v18, 16, v42
	v_and_b32_e32 v19, 0xffff0000, v42
	v_lshlrev_b32_e32 v20, 16, v43
	v_and_b32_e32 v21, 0xffff0000, v43
	v_pk_add_f32 v[6:7], v[6:7], v[14:15]
	v_pk_add_f32 v[8:9], v[8:9], v[16:17]
	v_pk_add_f32 v[10:11], v[10:11], v[18:19]
	v_pk_add_f32 v[12:13], v[12:13], v[20:21]
	s_bfm_b64 exec, 32, 32
	v_lshlrev_b32_e32 v14, 16, v44
	v_and_b32_e32 v15, 0xffff0000, v44
	v_lshlrev_b32_e32 v16, 16, v45
	v_and_b32_e32 v17, 0xffff0000, v45
	v_lshlrev_b32_e32 v18, 16, v46
	v_and_b32_e32 v19, 0xffff0000, v46
	v_lshlrev_b32_e32 v20, 16, v47
	v_and_b32_e32 v21, 0xffff0000, v47
	v_pk_add_f32 v[6:7], v[6:7], v[14:15]
	v_pk_add_f32 v[8:9], v[8:9], v[16:17]
	v_pk_add_f32 v[10:11], v[10:11], v[18:19]
	v_pk_add_f32 v[12:13], v[12:13], v[20:21]
	v_lshlrev_b32_e32 v14, 16, v48
	v_and_b32_e32 v15, 0xffff0000, v48
	v_lshlrev_b32_e32 v16, 16, v49
	v_and_b32_e32 v17, 0xffff0000, v49
	v_lshlrev_b32_e32 v18, 16, v50
	v_and_b32_e32 v19, 0xffff0000, v50
	v_lshlrev_b32_e32 v20, 16, v51
	v_and_b32_e32 v21, 0xffff0000, v51
	v_pk_add_f32 v[6:7], v[6:7], v[14:15]
	v_pk_add_f32 v[8:9], v[8:9], v[16:17]
	v_pk_add_f32 v[10:11], v[10:11], v[18:19]
	v_pk_add_f32 v[12:13], v[12:13], v[20:21]
	s_bfm_b64 exec, 16, 48
	v_lshlrev_b32_e32 v14, 16, v52
	v_and_b32_e32 v15, 0xffff0000, v52
	v_lshlrev_b32_e32 v16, 16, v53
	v_and_b32_e32 v17, 0xffff0000, v53
	v_lshlrev_b32_e32 v18, 16, v54
; __device__ __forceinline__ void unpack8(const u32x4 v, float* a) { a[0] = bflo(v.x); a[1] = bfhi(v.x); a[2] = bflo(v.y); a[3] = bfhi(v.y); a[4] = bflo(v.z); a[5] = bfhi(v.z); a[6] = bflo(v.w); a[7] = bfhi(v.w); }
; __device__ __forceinline__ void pool_block(const bf16_t* Z, bf16_t* A2, int row0, int lane) {
;     ...
;     for (int i = 0; i < 16; ++i) { const int t = t0 + i;
;         int lo = t - hw; if (lo < 0) lo = 0; int hi2 = t + hw - 1; if (hi2 > S - 1) hi2 = S - 1;
;         const float inv = 1.0f / (float)(hi2 - lo + 1);
;         float self[8]; unpack8(*(const u32x4*)(base + (size_t)t * NZ), self);
;         u32x4 o; o.x = pk2(sum[0] * inv - self[0], sum[1] * inv - self[1]); o.y = pk2(sum[2] * inv - self[2], sum[3] * inv - self[3]);
;         o.z = pk2(sum[4] * inv - self[4], sum[5] * inv - self[5]); o.w = pk2(sum[6] * inv - self[6], sum[7] * inv - self[7]);
;         *(u32x4*)(A2 + (size_t)(sb + t) * DM + 512 + lane * 8) = o;
;         const int radd = t + hw, rsub = t - hw;
;         if (radd < S) { unpack8(*(const u32x4*)(base + (size_t)radd * NZ), tmp);
; #pragma unroll
;             for (int e = 0; e < 8; ++e) sum[e] += tmp[e]; }
;         if (rsub >= 0) { unpack8(*(const u32x4*)(base + (size_t)rsub * NZ), tmp);
; #pragma unroll
;             for (int e = 0; e < 8; ++e) sum[e] -= tmp[e]; }
	v_and_b32_e32 v19, 0xffff0000, v54
	v_lshlrev_b32_e32 v20, 16, v55
	v_and_b32_e32 v21, 0xffff0000, v55
	v_pk_add_f32 v[6:7], v[6:7], v[14:15]
	v_pk_add_f32 v[8:9], v[8:9], v[16:17]
	v_pk_add_f32 v[10:11], v[10:11], v[18:19]
	v_pk_add_f32 v[12:13], v[12:13], v[20:21]
	v_lshlrev_b32_e32 v14, 16, v56
	v_and_b32_e32 v15, 0xffff0000, v56
	v_lshlrev_b32_e32 v16, 16, v57
	v_and_b32_e32 v17, 0xffff0000, v57
	v_lshlrev_b32_e32 v18, 16, v58
	v_and_b32_e32 v19, 0xffff0000, v58
	v_lshlrev_b32_e32 v20, 16, v59
	v_and_b32_e32 v21, 0xffff0000, v59
	v_pk_add_f32 v[6:7], v[6:7], v[14:15]
	v_pk_add_f32 v[8:9], v[8:9], v[16:17]
	v_pk_add_f32 v[10:11], v[10:11], v[18:19]
	v_pk_add_f32 v[12:13], v[12:13], v[20:21]
	v_lshlrev_b32_e32 v14, 16, v60
	v_and_b32_e32 v15, 0xffff0000, v60
	v_lshlrev_b32_e32 v16, 16, v61
	v_and_b32_e32 v17, 0xffff0000, v61
	v_lshlrev_b32_e32 v18, 16, v62
	v_and_b32_e32 v19, 0xffff0000, v62
	v_lshlrev_b32_e32 v20, 16, v63
	v_and_b32_e32 v21, 0xffff0000, v63
	v_pk_add_f32 v[6:7], v[6:7], v[14:15]
	v_pk_add_f32 v[8:9], v[8:9], v[16:17]
	v_pk_add_f32 v[10:11], v[10:11], v[18:19]
	v_pk_add_f32 v[12:13], v[12:13], v[20:21]
	v_lshlrev_b32_e32 v14, 16, v64
	v_and_b32_e32 v15, 0xffff0000, v64
	v_lshlrev_b32_e32 v16, 16, v65
	v_and_b32_e32 v17, 0xffff0000, v65
	v_lshlrev_b32_e32 v18, 16, v66
	v_and_b32_e32 v19, 0xffff0000, v66
	v_lshlrev_b32_e32 v20, 16, v67
	v_and_b32_e32 v21, 0xffff0000, v67
	v_pk_add_f32 v[6:7], v[6:7], v[14:15]
	v_pk_add_f32 v[8:9], v[8:9], v[16:17]
	v_pk_add_f32 v[10:11], v[10:11], v[18:19]
	v_pk_add_f32 v[12:13], v[12:13], v[20:21]
	s_mov_b64 exec, -1
	v_lshlrev_b32_e32 v14, 16, v36
	v_and_b32_e32 v15, 0xffff0000, v36
	v_lshlrev_b32_e32 v16, 16, v37
	v_and_b32_e32 v17, 0xffff0000, v37
	v_lshlrev_b32_e32 v18, 16, v38
	v_and_b32_e32 v19, 0xffff0000, v38
	v_lshlrev_b32_e32 v20, 16, v39
	v_and_b32_e32 v21, 0xffff0000, v39
	v_pk_fma_f32 v[14:15], v[6:7], v[24:25], v[14:15] op_sel_hi:[1,0,1] neg_lo:[0,0,1] neg_hi:[0,0,1]
	v_pk_fma_f32 v[16:17], v[8:9], v[24:25], v[16:17] op_sel_hi:[1,0,1] neg_lo:[0,0,1] neg_hi:[0,0,1]
	v_pk_fma_f32 v[18:19], v[10:11], v[24:25], v[18:19] op_sel_hi:[1,0,1] neg_lo:[0,0,1] neg_hi:[0,0,1]
	v_pk_fma_f32 v[20:21], v[12:13], v[24:25], v[20:21] op_sel_hi:[1,0,1] neg_lo:[0,0,1] neg_hi:[0,0,1]
	v_cvt_pk_bf16_f32 v132, v14, v15
	v_cvt_pk_bf16_f32 v133, v16, v17
	v_cvt_pk_bf16_f32 v134, v18, v19
	v_cvt_pk_bf16_f32 v135, v20, v21
	global_store_dwordx4 v143, v[132:135], s[8:9]
	v_add_u32_e32 v143, 0x800, v143
	v_lshlrev_b32_e32 v14, 16, v68
	v_and_b32_e32 v15, 0xffff0000, v68
	v_lshlrev_b32_e32 v16, 16, v69
	v_and_b32_e32 v17, 0xffff0000, v69
	v_lshlrev_b32_e32 v18, 16, v70
	v_and_b32_e32 v19, 0xffff0000, v70
	v_lshlrev_b32_e32 v20, 16, v71
	v_and_b32_e32 v21, 0xffff0000, v71
	v_pk_add_f32 v[6:7], v[6:7], v[14:15]
	v_pk_add_f32 v[8:9], v[8:9], v[16:17]
	v_pk_add_f32 v[10:11], v[10:11], v[18:19]
	v_pk_add_f32 v[12:13], v[12:13], v[20:21]
	v_lshlrev_b32_e32 v14, 16, v100
	v_and_b32_e32 v15, 0xffff0000, v100
	v_lshlrev_b32_e32 v16, 16, v101
	v_and_b32_e32 v17, 0xffff0000, v101
	v_lshlrev_b32_e32 v18, 16, v102
	v_and_b32_e32 v19, 0xffff0000, v102
	v_lshlrev_b32_e32 v20, 16, v103
	v_and_b32_e32 v21, 0xffff0000, v103
	v_pk_add_f32 v[6:7], v[6:7], v[14:15] neg_lo:[0,1] neg_hi:[0,1]
	v_pk_add_f32 v[8:9], v[8:9], v[16:17] neg_lo:[0,1] neg_hi:[0,1]
	v_pk_add_f32 v[10:11], v[10:11], v[18:19] neg_lo:[0,1] neg_hi:[0,1]
	v_pk_add_f32 v[12:13], v[12:13], v[20:21] neg_lo:[0,1] neg_hi:[0,1]
	global_load_dwordx4 v[36:39], v140, s[6:7]
	global_load_dwordx4 v[68:71], v141, s[6:7]
	global_load_dwordx4 v[100:103], v142, s[6:7]
	v_add_u32_e32 v140, 0x1000, v140
	v_add_u32_e32 v141, 0x1000, v141
	v_add_u32_e32 v142, 0x1000, v142
	v_lshlrev_b32_e32 v14, 16, v40
	v_and_b32_e32 v15, 0xffff0000, v40
	v_lshlrev_b32_e32 v16, 16, v41
	v_and_b32_e32 v17, 0xffff0000, v41
	v_lshlrev_b32_e32 v18, 16, v42
	v_and_b32_e32 v19, 0xffff0000, v42
	v_lshlrev_b32_e32 v20, 16, v43
	v_and_b32_e32 v21, 0xffff0000, v43
	v_pk_fma_f32 v[14:15], v[6:7], v[24:25], v[14:15] op_sel_hi:[1,0,1] neg_lo:[0,0,1] neg_hi:[0,0,1]
	v_pk_fma_f32 v[16:17], v[8:9], v[24:25], v[16:17] op_sel_hi:[1,0,1] neg_lo:[0,0,1] neg_hi:[0,0,1]
	v_pk_fma_f32 v[18:19], v[10:11], v[24:25], v[18:19] op_sel_hi:[1,0,1] neg_lo:[0,0,1] neg_hi:[0,0,1]
	v_pk_fma_f32 v[20:21], v[12:13], v[24:25], v[20:21] op_sel_hi:[1,0,1] neg_lo:[0,0,1] neg_hi:[0,0,1]
	v_cvt_pk_bf16_f32 v136, v14, v15
	v_cvt_pk_bf16_f32 v137, v16, v17
	v_cvt_pk_bf16_f32 v138, v18, v19
	v_cvt_pk_bf16_f32 v139, v20, v21
	global_store_dwordx4 v143, v[136:139], s[8:9]
	v_add_u32_e32 v143, 0x800, v143
	v_lshlrev_b32_e32 v14, 16, v72
	v_and_b32_e32 v15, 0xffff0000, v72
	v_lshlrev_b32_e32 v16, 16, v73
	v_and_b32_e32 v17, 0xffff0000, v73
	v_lshlrev_b32_e32 v18, 16, v74
	v_and_b32_e32 v19, 0xffff0000, v74
	v_lshlrev_b32_e32 v20, 16, v75
	v_and_b32_e32 v21, 0xffff0000, v75
	v_pk_add_f32 v[6:7], v[6:7], v[14:15]
	v_pk_add_f32 v[8:9], v[8:9], v[16:17]
	v_pk_add_f32 v[10:11], v[10:11], v[18:19]
	v_pk_add_f32 v[12:13], v[12:13], v[20:21]
	v_lshlrev_b32_e32 v14, 16, v104
	v_and_b32_e32 v15, 0xffff0000, v104
	v_lshlrev_b32_e32 v16, 16, v105
	v_and_b32_e32 v17, 0xffff0000, v105
	v_lshlrev_b32_e32 v18, 16, v106
	v_and_b32_e32 v19, 0xffff0000, v106
	v_lshlrev_b32_e32 v20, 16, v107
	v_and_b32_e32 v21, 0xffff0000, v107
	v_pk_add_f32 v[6:7], v[6:7], v[14:15] neg_lo:[0,1] neg_hi:[0,1]
	v_pk_add_f32 v[8:9], v[8:9], v[16:17] neg_lo:[0,1] neg_hi:[0,1]
	v_pk_add_f32 v[10:11], v[10:11], v[18:19] neg_lo:[0,1] neg_hi:[0,1]
	v_pk_add_f32 v[12:13], v[12:13], v[20:21] neg_lo:[0,1] neg_hi:[0,1]
	global_load_dwordx4 v[40:43], v140, s[6:7]
; __device__ __forceinline__ void unpack8(const u32x4 v, float* a) { a[0] = bflo(v.x); a[1] = bfhi(v.x); a[2] = bflo(v.y); a[3] = bfhi(v.y); a[4] = bflo(v.z); a[5] = bfhi(v.z); a[6] = bflo(v.w); a[7] = bfhi(v.w); }
; __device__ __forceinline__ void pool_block(const bf16_t* Z, bf16_t* A2, int row0, int lane) {
;     ...
;     for (int i = 0; i < 16; ++i) { const int t = t0 + i;
;         int lo = t - hw; if (lo < 0) lo = 0; int hi2 = t + hw - 1; if (hi2 > S - 1) hi2 = S - 1;
;         const float inv = 1.0f / (float)(hi2 - lo + 1);
;         float self[8]; unpack8(*(const u32x4*)(base + (size_t)t * NZ), self);
;         u32x4 o; o.x = pk2(sum[0] * inv - self[0], sum[1] * inv - self[1]); o.y = pk2(sum[2] * inv - self[2], sum[3] * inv - self[3]);
;         o.z = pk2(sum[4] * inv - self[4], sum[5] * inv - self[5]); o.w = pk2(sum[6] * inv - self[6], sum[7] * inv - self[7]);
;         *(u32x4*)(A2 + (size_t)(sb + t) * DM + 512 + lane * 8) = o;
;         const int radd = t + hw, rsub = t - hw;
;         if (radd < S) { unpack8(*(const u32x4*)(base + (size_t)radd * NZ), tmp);
; #pragma unroll
;             for (int e = 0; e < 8; ++e) sum[e] += tmp[e]; }
;         if (rsub >= 0) { unpack8(*(const u32x4*)(base + (size_t)rsub * NZ), tmp);
; #pragma unroll
;             for (int e = 0; e < 8; ++e) sum[e] -= tmp[e]; }
	global_load_dwordx4 v[72:75], v141, s[6:7]
	global_load_dwordx4 v[104:107], v142, s[6:7]
	v_add_u32_e32 v140, 0x1000, v140
	v_add_u32_e32 v141, 0x1000, v141
	v_add_u32_e32 v142, 0x1000, v142
	v_lshlrev_b32_e32 v14, 16, v44
	v_and_b32_e32 v15, 0xffff0000, v44
	v_lshlrev_b32_e32 v16, 16, v45
	v_and_b32_e32 v17, 0xffff0000, v45
	v_lshlrev_b32_e32 v18, 16, v46
	v_and_b32_e32 v19, 0xffff0000, v46
	v_lshlrev_b32_e32 v20, 16, v47
	v_and_b32_e32 v21, 0xffff0000, v47
	v_pk_fma_f32 v[14:15], v[6:7], v[24:25], v[14:15] op_sel_hi:[1,0,1] neg_lo:[0,0,1] neg_hi:[0,0,1]
	v_pk_fma_f32 v[16:17], v[8:9], v[24:25], v[16:17] op_sel_hi:[1,0,1] neg_lo:[0,0,1] neg_hi:[0,0,1]
	v_pk_fma_f32 v[18:19], v[10:11], v[24:25], v[18:19] op_sel_hi:[1,0,1] neg_lo:[0,0,1] neg_hi:[0,0,1]
	v_pk_fma_f32 v[20:21], v[12:13], v[24:25], v[20:21] op_sel_hi:[1,0,1] neg_lo:[0,0,1] neg_hi:[0,0,1]
	v_cvt_pk_bf16_f32 v132, v14, v15
	v_cvt_pk_bf16_f32 v133, v16, v17
	v_cvt_pk_bf16_f32 v134, v18, v19
	v_cvt_pk_bf16_f32 v135, v20, v21
	global_store_dwordx4 v143, v[132:135], s[8:9]
	v_add_u32_e32 v143, 0x800, v143
	v_lshlrev_b32_e32 v14, 16, v76
	v_and_b32_e32 v15, 0xffff0000, v76
	v_lshlrev_b32_e32 v16, 16, v77
	v_and_b32_e32 v17, 0xffff0000, v77
	v_lshlrev_b32_e32 v18, 16, v78
	v_and_b32_e32 v19, 0xffff0000, v78
	v_lshlrev_b32_e32 v20, 16, v79
	v_and_b32_e32 v21, 0xffff0000, v79
	v_pk_add_f32 v[6:7], v[6:7], v[14:15]
	v_pk_add_f32 v[8:9], v[8:9], v[16:17]
	v_pk_add_f32 v[10:11], v[10:11], v[18:19]
	v_pk_add_f32 v[12:13], v[12:13], v[20:21]
	v_lshlrev_b32_e32 v14, 16, v108
	v_and_b32_e32 v15, 0xffff0000, v108
	v_lshlrev_b32_e32 v16, 16, v109
	v_and_b32_e32 v17, 0xffff0000, v109
	v_lshlrev_b32_e32 v18, 16, v110
	v_and_b32_e32 v19, 0xffff0000, v110
	v_lshlrev_b32_e32 v20, 16, v111
	v_and_b32_e32 v21, 0xffff0000, v111
	v_pk_add_f32 v[6:7], v[6:7], v[14:15] neg_lo:[0,1] neg_hi:[0,1]
	v_pk_add_f32 v[8:9], v[8:9], v[16:17] neg_lo:[0,1] neg_hi:[0,1]
	v_pk_add_f32 v[10:11], v[10:11], v[18:19] neg_lo:[0,1] neg_hi:[0,1]
	v_pk_add_f32 v[12:13], v[12:13], v[20:21] neg_lo:[0,1] neg_hi:[0,1]
	global_load_dwordx4 v[44:47], v140, s[6:7]
	global_load_dwordx4 v[76:79], v141, s[6:7]
	global_load_dwordx4 v[108:111], v142, s[6:7]
	v_add_u32_e32 v140, 0x1000, v140
	v_add_u32_e32 v141, 0x1000, v141
	v_add_u32_e32 v142, 0x1000, v142
	v_lshlrev_b32_e32 v14, 16, v48
	v_and_b32_e32 v15, 0xffff0000, v48
	v_lshlrev_b32_e32 v16, 16, v49
	v_and_b32_e32 v17, 0xffff0000, v49
	v_lshlrev_b32_e32 v18, 16, v50
	v_and_b32_e32 v19, 0xffff0000, v50
	v_lshlrev_b32_e32 v20, 16, v51
	v_and_b32_e32 v21, 0xffff0000, v51
	v_pk_fma_f32 v[14:15], v[6:7], v[24:25], v[14:15] op_sel_hi:[1,0,1] neg_lo:[0,0,1] neg_hi:[0,0,1]
	v_pk_fma_f32 v[16:17], v[8:9], v[24:25], v[16:17] op_sel_hi:[1,0,1] neg_lo:[0,0,1] neg_hi:[0,0,1]
	v_pk_fma_f32 v[18:19], v[10:11], v[24:25], v[18:19] op_sel_hi:[1,0,1] neg_lo:[0,0,1] neg_hi:[0,0,1]
	v_pk_fma_f32 v[20:21], v[12:13], v[24:25], v[20:21] op_sel_hi:[1,0,1] neg_lo:[0,0,1] neg_hi:[0,0,1]
	v_cvt_pk_bf16_f32 v136, v14, v15
	v_cvt_pk_bf16_f32 v137, v16, v17
	v_cvt_pk_bf16_f32 v138, v18, v19
	v_cvt_pk_bf16_f32 v139, v20, v21
	global_store_dwordx4 v143, v[136:139], s[8:9]
	v_add_u32_e32 v143, 0x800, v143
	v_lshlrev_b32_e32 v14, 16, v80
	v_and_b32_e32 v15, 0xffff0000, v80
	v_lshlrev_b32_e32 v16, 16, v81
	v_and_b32_e32 v17, 0xffff0000, v81
	v_lshlrev_b32_e32 v18, 16, v82
	v_and_b32_e32 v19, 0xffff0000, v82
	v_lshlrev_b32_e32 v20, 16, v83
	v_and_b32_e32 v21, 0xffff0000, v83
	v_pk_add_f32 v[6:7], v[6:7], v[14:15]
	v_pk_add_f32 v[8:9], v[8:9], v[16:17]
	v_pk_add_f32 v[10:11], v[10:11], v[18:19]
	v_pk_add_f32 v[12:13], v[12:13], v[20:21]
	v_lshlrev_b32_e32 v14, 16, v112
	v_and_b32_e32 v15, 0xffff0000, v112
	v_lshlrev_b32_e32 v16, 16, v113
	v_and_b32_e32 v17, 0xffff0000, v113
	v_lshlrev_b32_e32 v18, 16, v114
	v_and_b32_e32 v19, 0xffff0000, v114
	v_lshlrev_b32_e32 v20, 16, v115
	v_and_b32_e32 v21, 0xffff0000, v115
	v_pk_add_f32 v[6:7], v[6:7], v[14:15] neg_lo:[0,1] neg_hi:[0,1]
	v_pk_add_f32 v[8:9], v[8:9], v[16:17] neg_lo:[0,1] neg_hi:[0,1]
	v_pk_add_f32 v[10:11], v[10:11], v[18:19] neg_lo:[0,1] neg_hi:[0,1]
	v_pk_add_f32 v[12:13], v[12:13], v[20:21] neg_lo:[0,1] neg_hi:[0,1]
	global_load_dwordx4 v[48:51], v140, s[6:7]
	global_load_dwordx4 v[80:83], v141, s[6:7]
	global_load_dwordx4 v[112:115], v142, s[6:7]
	v_add_u32_e32 v140, 0x1000, v140
	v_add_u32_e32 v141, 0x1000, v141
	v_add_u32_e32 v142, 0x1000, v142
	v_lshlrev_b32_e32 v14, 16, v52
	v_and_b32_e32 v15, 0xffff0000, v52
	v_lshlrev_b32_e32 v16, 16, v53
	v_and_b32_e32 v17, 0xffff0000, v53
	v_lshlrev_b32_e32 v18, 16, v54
	v_and_b32_e32 v19, 0xffff0000, v54
	v_lshlrev_b32_e32 v20, 16, v55
	v_and_b32_e32 v21, 0xffff0000, v55
	v_pk_fma_f32 v[14:15], v[6:7], v[24:25], v[14:15] op_sel_hi:[1,0,1] neg_lo:[0,0,1] neg_hi:[0,0,1]
	v_pk_fma_f32 v[16:17], v[8:9], v[24:25], v[16:17] op_sel_hi:[1,0,1] neg_lo:[0,0,1] neg_hi:[0,0,1]
	v_pk_fma_f32 v[18:19], v[10:11], v[24:25], v[18:19] op_sel_hi:[1,0,1] neg_lo:[0,0,1] neg_hi:[0,0,1]
	v_pk_fma_f32 v[20:21], v[12:13], v[24:25], v[20:21] op_sel_hi:[1,0,1] neg_lo:[0,0,1] neg_hi:[0,0,1]
	v_cvt_pk_bf16_f32 v132, v14, v15
	v_cvt_pk_bf16_f32 v133, v16, v17
	v_cvt_pk_bf16_f32 v134, v18, v19
	v_cvt_pk_bf16_f32 v135, v20, v21
	global_store_dwordx4 v143, v[132:135], s[8:9]
	v_add_u32_e32 v143, 0x800, v143
	v_lshlrev_b32_e32 v14, 16, v84
	v_and_b32_e32 v15, 0xffff0000, v84
	v_lshlrev_b32_e32 v16, 16, v85
	v_and_b32_e32 v17, 0xffff0000, v85
	v_lshlrev_b32_e32 v18, 16, v86
	v_and_b32_e32 v19, 0xffff0000, v86
	v_lshlrev_b32_e32 v20, 16, v87
	v_and_b32_e32 v21, 0xffff0000, v87
	v_pk_add_f32 v[6:7], v[6:7], v[14:15]
	v_pk_add_f32 v[8:9], v[8:9], v[16:17]
; __device__ __forceinline__ void unpack8(const u32x4 v, float* a) { a[0] = bflo(v.x); a[1] = bfhi(v.x); a[2] = bflo(v.y); a[3] = bfhi(v.y); a[4] = bflo(v.z); a[5] = bfhi(v.z); a[6] = bflo(v.w); a[7] = bfhi(v.w); }
; __device__ __forceinline__ void pool_block(const bf16_t* Z, bf16_t* A2, int row0, int lane) {
;     ...
;     for (int i = 0; i < 16; ++i) { const int t = t0 + i;
;         int lo = t - hw; if (lo < 0) lo = 0; int hi2 = t + hw - 1; if (hi2 > S - 1) hi2 = S - 1;
;         const float inv = 1.0f / (float)(hi2 - lo + 1);
;         float self[8]; unpack8(*(const u32x4*)(base + (size_t)t * NZ), self);
;         u32x4 o; o.x = pk2(sum[0] * inv - self[0], sum[1] * inv - self[1]); o.y = pk2(sum[2] * inv - self[2], sum[3] * inv - self[3]);
;         o.z = pk2(sum[4] * inv - self[4], sum[5] * inv - self[5]); o.w = pk2(sum[6] * inv - self[6], sum[7] * inv - self[7]);
;         *(u32x4*)(A2 + (size_t)(sb + t) * DM + 512 + lane * 8) = o;
;         const int radd = t + hw, rsub = t - hw;
;         if (radd < S) { unpack8(*(const u32x4*)(base + (size_t)radd * NZ), tmp);
; #pragma unroll
;             for (int e = 0; e < 8; ++e) sum[e] += tmp[e]; }
;         if (rsub >= 0) { unpack8(*(const u32x4*)(base + (size_t)rsub * NZ), tmp);
; #pragma unroll
;             for (int e = 0; e < 8; ++e) sum[e] -= tmp[e]; }
	v_pk_add_f32 v[10:11], v[10:11], v[18:19]
	v_pk_add_f32 v[12:13], v[12:13], v[20:21]
	v_lshlrev_b32_e32 v14, 16, v116
	v_and_b32_e32 v15, 0xffff0000, v116
	v_lshlrev_b32_e32 v16, 16, v117
	v_and_b32_e32 v17, 0xffff0000, v117
	v_lshlrev_b32_e32 v18, 16, v118
	v_and_b32_e32 v19, 0xffff0000, v118
	v_lshlrev_b32_e32 v20, 16, v119
	v_and_b32_e32 v21, 0xffff0000, v119
	v_pk_add_f32 v[6:7], v[6:7], v[14:15] neg_lo:[0,1] neg_hi:[0,1]
	v_pk_add_f32 v[8:9], v[8:9], v[16:17] neg_lo:[0,1] neg_hi:[0,1]
	v_pk_add_f32 v[10:11], v[10:11], v[18:19] neg_lo:[0,1] neg_hi:[0,1]
	v_pk_add_f32 v[12:13], v[12:13], v[20:21] neg_lo:[0,1] neg_hi:[0,1]
	global_load_dwordx4 v[52:55], v140, s[6:7]
	global_load_dwordx4 v[84:87], v141, s[6:7]
	global_load_dwordx4 v[116:119], v142, s[6:7]
	v_add_u32_e32 v140, 0x1000, v140
	v_add_u32_e32 v141, 0x1000, v141
	v_add_u32_e32 v142, 0x1000, v142
	v_lshlrev_b32_e32 v14, 16, v56
	v_and_b32_e32 v15, 0xffff0000, v56
	v_lshlrev_b32_e32 v16, 16, v57
	v_and_b32_e32 v17, 0xffff0000, v57
	v_lshlrev_b32_e32 v18, 16, v58
	v_and_b32_e32 v19, 0xffff0000, v58
	v_lshlrev_b32_e32 v20, 16, v59
	v_and_b32_e32 v21, 0xffff0000, v59
	v_pk_fma_f32 v[14:15], v[6:7], v[24:25], v[14:15] op_sel_hi:[1,0,1] neg_lo:[0,0,1] neg_hi:[0,0,1]
	v_pk_fma_f32 v[16:17], v[8:9], v[24:25], v[16:17] op_sel_hi:[1,0,1] neg_lo:[0,0,1] neg_hi:[0,0,1]
	v_pk_fma_f32 v[18:19], v[10:11], v[24:25], v[18:19] op_sel_hi:[1,0,1] neg_lo:[0,0,1] neg_hi:[0,0,1]
	v_pk_fma_f32 v[20:21], v[12:13], v[24:25], v[20:21] op_sel_hi:[1,0,1] neg_lo:[0,0,1] neg_hi:[0,0,1]
	v_cvt_pk_bf16_f32 v136, v14, v15
	v_cvt_pk_bf16_f32 v137, v16, v17
	v_cvt_pk_bf16_f32 v138, v18, v19
	v_cvt_pk_bf16_f32 v139, v20, v21
	global_store_dwordx4 v143, v[136:139], s[8:9]
	v_add_u32_e32 v143, 0x800, v143
	v_lshlrev_b32_e32 v14, 16, v88
	v_and_b32_e32 v15, 0xffff0000, v88
	v_lshlrev_b32_e32 v16, 16, v89
	v_and_b32_e32 v17, 0xffff0000, v89
	v_lshlrev_b32_e32 v18, 16, v90
	v_and_b32_e32 v19, 0xffff0000, v90
	v_lshlrev_b32_e32 v20, 16, v91
	v_and_b32_e32 v21, 0xffff0000, v91
	v_pk_add_f32 v[6:7], v[6:7], v[14:15]
	v_pk_add_f32 v[8:9], v[8:9], v[16:17]
	v_pk_add_f32 v[10:11], v[10:11], v[18:19]
	v_pk_add_f32 v[12:13], v[12:13], v[20:21]
	v_lshlrev_b32_e32 v14, 16, v120
	v_and_b32_e32 v15, 0xffff0000, v120
	v_lshlrev_b32_e32 v16, 16, v121
	v_and_b32_e32 v17, 0xffff0000, v121
	v_lshlrev_b32_e32 v18, 16, v122
	v_and_b32_e32 v19, 0xffff0000, v122
	v_lshlrev_b32_e32 v20, 16, v123
	v_and_b32_e32 v21, 0xffff0000, v123
	v_pk_add_f32 v[6:7], v[6:7], v[14:15] neg_lo:[0,1] neg_hi:[0,1]
	v_pk_add_f32 v[8:9], v[8:9], v[16:17] neg_lo:[0,1] neg_hi:[0,1]
	v_pk_add_f32 v[10:11], v[10:11], v[18:19] neg_lo:[0,1] neg_hi:[0,1]
	v_pk_add_f32 v[12:13], v[12:13], v[20:21] neg_lo:[0,1] neg_hi:[0,1]
	global_load_dwordx4 v[56:59], v140, s[6:7]
	global_load_dwordx4 v[88:91], v141, s[6:7]
	global_load_dwordx4 v[120:123], v142, s[6:7]
	v_add_u32_e32 v140, 0x1000, v140
	v_add_u32_e32 v141, 0x1000, v141
	v_add_u32_e32 v142, 0x1000, v142
	v_lshlrev_b32_e32 v14, 16, v60
	v_and_b32_e32 v15, 0xffff0000, v60
	v_lshlrev_b32_e32 v16, 16, v61
	v_and_b32_e32 v17, 0xffff0000, v61
	v_lshlrev_b32_e32 v18, 16, v62
	v_and_b32_e32 v19, 0xffff0000, v62
	v_lshlrev_b32_e32 v20, 16, v63
	v_and_b32_e32 v21, 0xffff0000, v63
	v_pk_fma_f32 v[14:15], v[6:7], v[24:25], v[14:15] op_sel_hi:[1,0,1] neg_lo:[0,0,1] neg_hi:[0,0,1]
	v_pk_fma_f32 v[16:17], v[8:9], v[24:25], v[16:17] op_sel_hi:[1,0,1] neg_lo:[0,0,1] neg_hi:[0,0,1]
	v_pk_fma_f32 v[18:19], v[10:11], v[24:25], v[18:19] op_sel_hi:[1,0,1] neg_lo:[0,0,1] neg_hi:[0,0,1]
	v_pk_fma_f32 v[20:21], v[12:13], v[24:25], v[20:21] op_sel_hi:[1,0,1] neg_lo:[0,0,1] neg_hi:[0,0,1]
	v_cvt_pk_bf16_f32 v132, v14, v15
	v_cvt_pk_bf16_f32 v133, v16, v17
	v_cvt_pk_bf16_f32 v134, v18, v19
	v_cvt_pk_bf16_f32 v135, v20, v21
	global_store_dwordx4 v143, v[132:135], s[8:9]
	v_add_u32_e32 v143, 0x800, v143
	v_lshlrev_b32_e32 v14, 16, v92
	v_and_b32_e32 v15, 0xffff0000, v92
	v_lshlrev_b32_e32 v16, 16, v93
	v_and_b32_e32 v17, 0xffff0000, v93
	v_lshlrev_b32_e32 v18, 16, v94
	v_and_b32_e32 v19, 0xffff0000, v94
	v_lshlrev_b32_e32 v20, 16, v95
	v_and_b32_e32 v21, 0xffff0000, v95
	v_pk_add_f32 v[6:7], v[6:7], v[14:15]
	v_pk_add_f32 v[8:9], v[8:9], v[16:17]
	v_pk_add_f32 v[10:11], v[10:11], v[18:19]
	v_pk_add_f32 v[12:13], v[12:13], v[20:21]
	v_lshlrev_b32_e32 v14, 16, v124
	v_and_b32_e32 v15, 0xffff0000, v124
	v_lshlrev_b32_e32 v16, 16, v125
	v_and_b32_e32 v17, 0xffff0000, v125
	v_lshlrev_b32_e32 v18, 16, v126
	v_and_b32_e32 v19, 0xffff0000, v126
	v_lshlrev_b32_e32 v20, 16, v127
	v_and_b32_e32 v21, 0xffff0000, v127
	v_pk_add_f32 v[6:7], v[6:7], v[14:15] neg_lo:[0,1] neg_hi:[0,1]
	v_pk_add_f32 v[8:9], v[8:9], v[16:17] neg_lo:[0,1] neg_hi:[0,1]
	v_pk_add_f32 v[10:11], v[10:11], v[18:19] neg_lo:[0,1] neg_hi:[0,1]
	v_pk_add_f32 v[12:13], v[12:13], v[20:21] neg_lo:[0,1] neg_hi:[0,1]
	global_load_dwordx4 v[60:63], v140, s[6:7]
	global_load_dwordx4 v[92:95], v141, s[6:7]
	global_load_dwordx4 v[124:127], v142, s[6:7]
	v_add_u32_e32 v140, 0x1000, v140
	v_add_u32_e32 v141, 0x1000, v141
	v_add_u32_e32 v142, 0x1000, v142
	v_lshlrev_b32_e32 v14, 16, v64
	v_and_b32_e32 v15, 0xffff0000, v64
	v_lshlrev_b32_e32 v16, 16, v65
	v_and_b32_e32 v17, 0xffff0000, v65
	v_lshlrev_b32_e32 v18, 16, v66
	v_and_b32_e32 v19, 0xffff0000, v66
	v_lshlrev_b32_e32 v20, 16, v67
	v_and_b32_e32 v21, 0xffff0000, v67
	v_pk_fma_f32 v[14:15], v[6:7], v[24:25], v[14:15] op_sel_hi:[1,0,1] neg_lo:[0,0,1] neg_hi:[0,0,1]
	v_pk_fma_f32 v[16:17], v[8:9], v[24:25], v[16:17] op_sel_hi:[1,0,1] neg_lo:[0,0,1] neg_hi:[0,0,1]
	v_pk_fma_f32 v[18:19], v[10:11], v[24:25], v[18:19] op_sel_hi:[1,0,1] neg_lo:[0,0,1] neg_hi:[0,0,1]
; __device__ __forceinline__ void unpack8(const u32x4 v, float* a) { a[0] = bflo(v.x); a[1] = bfhi(v.x); a[2] = bflo(v.y); a[3] = bfhi(v.y); a[4] = bflo(v.z); a[5] = bfhi(v.z); a[6] = bflo(v.w); a[7] = bfhi(v.w); }
; __device__ __forceinline__ void pool_block(const bf16_t* Z, bf16_t* A2, int row0, int lane) {
;     ...
;     for (int i = 0; i < 16; ++i) { const int t = t0 + i;
;         int lo = t - hw; if (lo < 0) lo = 0; int hi2 = t + hw - 1; if (hi2 > S - 1) hi2 = S - 1;
;         const float inv = 1.0f / (float)(hi2 - lo + 1);
;         float self[8]; unpack8(*(const u32x4*)(base + (size_t)t * NZ), self);
;         u32x4 o; o.x = pk2(sum[0] * inv - self[0], sum[1] * inv - self[1]); o.y = pk2(sum[2] * inv - self[2], sum[3] * inv - self[3]);
;         o.z = pk2(sum[4] * inv - self[4], sum[5] * inv - self[5]); o.w = pk2(sum[6] * inv - self[6], sum[7] * inv - self[7]);
;         *(u32x4*)(A2 + (size_t)(sb + t) * DM + 512 + lane * 8) = o;
;         const int radd = t + hw, rsub = t - hw;
;         if (radd < S) { unpack8(*(const u32x4*)(base + (size_t)radd * NZ), tmp);
; #pragma unroll
;             for (int e = 0; e < 8; ++e) sum[e] += tmp[e]; }
;         if (rsub >= 0) { unpack8(*(const u32x4*)(base + (size_t)rsub * NZ), tmp);
; #pragma unroll
;             for (int e = 0; e < 8; ++e) sum[e] -= tmp[e]; }
	v_pk_fma_f32 v[20:21], v[12:13], v[24:25], v[20:21] op_sel_hi:[1,0,1] neg_lo:[0,0,1] neg_hi:[0,0,1]
	v_cvt_pk_bf16_f32 v136, v14, v15
	v_cvt_pk_bf16_f32 v137, v16, v17
	v_cvt_pk_bf16_f32 v138, v18, v19
	v_cvt_pk_bf16_f32 v139, v20, v21
	global_store_dwordx4 v143, v[136:139], s[8:9]
	v_add_u32_e32 v143, 0x800, v143
	v_lshlrev_b32_e32 v14, 16, v96
	v_and_b32_e32 v15, 0xffff0000, v96
	v_lshlrev_b32_e32 v16, 16, v97
	v_and_b32_e32 v17, 0xffff0000, v97
	v_lshlrev_b32_e32 v18, 16, v98
	v_and_b32_e32 v19, 0xffff0000, v98
	v_lshlrev_b32_e32 v20, 16, v99
	v_and_b32_e32 v21, 0xffff0000, v99
	v_pk_add_f32 v[6:7], v[6:7], v[14:15]
	v_pk_add_f32 v[8:9], v[8:9], v[16:17]
	v_pk_add_f32 v[10:11], v[10:11], v[18:19]
	v_pk_add_f32 v[12:13], v[12:13], v[20:21]
	v_lshlrev_b32_e32 v14, 16, v128
	v_and_b32_e32 v15, 0xffff0000, v128
	v_lshlrev_b32_e32 v16, 16, v129
	v_and_b32_e32 v17, 0xffff0000, v129
	v_lshlrev_b32_e32 v18, 16, v130
	v_and_b32_e32 v19, 0xffff0000, v130
	v_lshlrev_b32_e32 v20, 16, v131
	v_and_b32_e32 v21, 0xffff0000, v131
	v_pk_add_f32 v[6:7], v[6:7], v[14:15] neg_lo:[0,1] neg_hi:[0,1]
	v_pk_add_f32 v[8:9], v[8:9], v[16:17] neg_lo:[0,1] neg_hi:[0,1]
	v_pk_add_f32 v[10:11], v[10:11], v[18:19] neg_lo:[0,1] neg_hi:[0,1]
	v_pk_add_f32 v[12:13], v[12:13], v[20:21] neg_lo:[0,1] neg_hi:[0,1]
	global_load_dwordx4 v[64:67], v140, s[6:7]
	global_load_dwordx4 v[96:99], v141, s[6:7]
	global_load_dwordx4 v[128:131], v142, s[6:7]
	v_add_u32_e32 v140, 0x1000, v140
	v_add_u32_e32 v141, 0x1000, v141
	v_add_u32_e32 v142, 0x1000, v142
	s_waitcnt vmcnt(28)
	v_lshlrev_b32_e32 v14, 16, v36
	v_and_b32_e32 v15, 0xffff0000, v36
	v_lshlrev_b32_e32 v16, 16, v37
	v_and_b32_e32 v17, 0xffff0000, v37
	v_lshlrev_b32_e32 v18, 16, v38
	v_and_b32_e32 v19, 0xffff0000, v38
	v_lshlrev_b32_e32 v20, 16, v39
	v_and_b32_e32 v21, 0xffff0000, v39
	v_pk_fma_f32 v[14:15], v[6:7], v[24:25], v[14:15] op_sel_hi:[1,0,1] neg_lo:[0,0,1] neg_hi:[0,0,1]
	v_pk_fma_f32 v[16:17], v[8:9], v[24:25], v[16:17] op_sel_hi:[1,0,1] neg_lo:[0,0,1] neg_hi:[0,0,1]
	v_pk_fma_f32 v[18:19], v[10:11], v[24:25], v[18:19] op_sel_hi:[1,0,1] neg_lo:[0,0,1] neg_hi:[0,0,1]
	v_pk_fma_f32 v[20:21], v[12:13], v[24:25], v[20:21] op_sel_hi:[1,0,1] neg_lo:[0,0,1] neg_hi:[0,0,1]
	v_cvt_pk_bf16_f32 v132, v14, v15
	v_cvt_pk_bf16_f32 v133, v16, v17
	v_cvt_pk_bf16_f32 v134, v18, v19
	v_cvt_pk_bf16_f32 v135, v20, v21
	global_store_dwordx4 v143, v[132:135], s[8:9]
	v_add_u32_e32 v143, 0x800, v143
	v_lshlrev_b32_e32 v14, 16, v68
	v_and_b32_e32 v15, 0xffff0000, v68
	v_lshlrev_b32_e32 v16, 16, v69
	v_and_b32_e32 v17, 0xffff0000, v69
	v_lshlrev_b32_e32 v18, 16, v70
	v_and_b32_e32 v19, 0xffff0000, v70
	v_lshlrev_b32_e32 v20, 16, v71
	v_and_b32_e32 v21, 0xffff0000, v71
	v_pk_add_f32 v[6:7], v[6:7], v[14:15]
	v_pk_add_f32 v[8:9], v[8:9], v[16:17]
	v_pk_add_f32 v[10:11], v[10:11], v[18:19]
	v_pk_add_f32 v[12:13], v[12:13], v[20:21]
	v_lshlrev_b32_e32 v14, 16, v100
	v_and_b32_e32 v15, 0xffff0000, v100
	v_lshlrev_b32_e32 v16, 16, v101
	v_and_b32_e32 v17, 0xffff0000, v101
	v_lshlrev_b32_e32 v18, 16, v102
	v_and_b32_e32 v19, 0xffff0000, v102
	v_lshlrev_b32_e32 v20, 16, v103
	v_and_b32_e32 v21, 0xffff0000, v103
	v_pk_add_f32 v[6:7], v[6:7], v[14:15] neg_lo:[0,1] neg_hi:[0,1]
	v_pk_add_f32 v[8:9], v[8:9], v[16:17] neg_lo:[0,1] neg_hi:[0,1]
	v_pk_add_f32 v[10:11], v[10:11], v[18:19] neg_lo:[0,1] neg_hi:[0,1]
	v_pk_add_f32 v[12:13], v[12:13], v[20:21] neg_lo:[0,1] neg_hi:[0,1]
	s_waitcnt vmcnt(25)
	v_lshlrev_b32_e32 v14, 16, v40
	v_and_b32_e32 v15, 0xffff0000, v40
	v_lshlrev_b32_e32 v16, 16, v41
	v_and_b32_e32 v17, 0xffff0000, v41
	v_lshlrev_b32_e32 v18, 16, v42
	v_and_b32_e32 v19, 0xffff0000, v42
	v_lshlrev_b32_e32 v20, 16, v43
	v_and_b32_e32 v21, 0xffff0000, v43
	v_pk_fma_f32 v[14:15], v[6:7], v[24:25], v[14:15] op_sel_hi:[1,0,1] neg_lo:[0,0,1] neg_hi:[0,0,1]
	v_pk_fma_f32 v[16:17], v[8:9], v[24:25], v[16:17] op_sel_hi:[1,0,1] neg_lo:[0,0,1] neg_hi:[0,0,1]
	v_pk_fma_f32 v[18:19], v[10:11], v[24:25], v[18:19] op_sel_hi:[1,0,1] neg_lo:[0,0,1] neg_hi:[0,0,1]
	v_pk_fma_f32 v[20:21], v[12:13], v[24:25], v[20:21] op_sel_hi:[1,0,1] neg_lo:[0,0,1] neg_hi:[0,0,1]
	v_cvt_pk_bf16_f32 v136, v14, v15
	v_cvt_pk_bf16_f32 v137, v16, v17
	v_cvt_pk_bf16_f32 v138, v18, v19
	v_cvt_pk_bf16_f32 v139, v20, v21
	global_store_dwordx4 v143, v[136:139], s[8:9]
	v_add_u32_e32 v143, 0x800, v143
	v_lshlrev_b32_e32 v14, 16, v72
	v_and_b32_e32 v15, 0xffff0000, v72
	v_lshlrev_b32_e32 v16, 16, v73
	v_and_b32_e32 v17, 0xffff0000, v73
	v_lshlrev_b32_e32 v18, 16, v74
	v_and_b32_e32 v19, 0xffff0000, v74
	v_lshlrev_b32_e32 v20, 16, v75
	v_and_b32_e32 v21, 0xffff0000, v75
	v_pk_add_f32 v[6:7], v[6:7], v[14:15]
	v_pk_add_f32 v[8:9], v[8:9], v[16:17]
	v_pk_add_f32 v[10:11], v[10:11], v[18:19]
	v_pk_add_f32 v[12:13], v[12:13], v[20:21]
	v_lshlrev_b32_e32 v14, 16, v104
	v_and_b32_e32 v15, 0xffff0000, v104
	v_lshlrev_b32_e32 v16, 16, v105
	v_and_b32_e32 v17, 0xffff0000, v105
	v_lshlrev_b32_e32 v18, 16, v106
	v_and_b32_e32 v19, 0xffff0000, v106
	v_lshlrev_b32_e32 v20, 16, v107
	v_and_b32_e32 v21, 0xffff0000, v107
	v_pk_add_f32 v[6:7], v[6:7], v[14:15] neg_lo:[0,1] neg_hi:[0,1]
	v_pk_add_f32 v[8:9], v[8:9], v[16:17] neg_lo:[0,1] neg_hi:[0,1]
	v_pk_add_f32 v[10:11], v[10:11], v[18:19] neg_lo:[0,1] neg_hi:[0,1]
	v_pk_add_f32 v[12:13], v[12:13], v[20:21] neg_lo:[0,1] neg_hi:[0,1]
	s_waitcnt vmcnt(22)
; __device__ __forceinline__ void unpack8(const u32x4 v, float* a) { a[0] = bflo(v.x); a[1] = bfhi(v.x); a[2] = bflo(v.y); a[3] = bfhi(v.y); a[4] = bflo(v.z); a[5] = bfhi(v.z); a[6] = bflo(v.w); a[7] = bfhi(v.w); }
; __device__ __forceinline__ void pool_block(const bf16_t* Z, bf16_t* A2, int row0, int lane) {
;     ...
;     for (int i = 0; i < 16; ++i) { const int t = t0 + i;
;         int lo = t - hw; if (lo < 0) lo = 0; int hi2 = t + hw - 1; if (hi2 > S - 1) hi2 = S - 1;
;         const float inv = 1.0f / (float)(hi2 - lo + 1);
;         float self[8]; unpack8(*(const u32x4*)(base + (size_t)t * NZ), self);
;         u32x4 o; o.x = pk2(sum[0] * inv - self[0], sum[1] * inv - self[1]); o.y = pk2(sum[2] * inv - self[2], sum[3] * inv - self[3]);
;         o.z = pk2(sum[4] * inv - self[4], sum[5] * inv - self[5]); o.w = pk2(sum[6] * inv - self[6], sum[7] * inv - self[7]);
;         *(u32x4*)(A2 + (size_t)(sb + t) * DM + 512 + lane * 8) = o;
;         const int radd = t + hw, rsub = t - hw;
;         if (radd < S) { unpack8(*(const u32x4*)(base + (size_t)radd * NZ), tmp);
; #pragma unroll
;             for (int e = 0; e < 8; ++e) sum[e] += tmp[e]; }
;         if (rsub >= 0) { unpack8(*(const u32x4*)(base + (size_t)rsub * NZ), tmp);
; #pragma unroll
;             for (int e = 0; e < 8; ++e) sum[e] -= tmp[e]; }
;     }
	v_lshlrev_b32_e32 v14, 16, v44
	v_and_b32_e32 v15, 0xffff0000, v44
	v_lshlrev_b32_e32 v16, 16, v45
	v_and_b32_e32 v17, 0xffff0000, v45
	v_lshlrev_b32_e32 v18, 16, v46
	v_and_b32_e32 v19, 0xffff0000, v46
	v_lshlrev_b32_e32 v20, 16, v47
	v_and_b32_e32 v21, 0xffff0000, v47
	v_pk_fma_f32 v[14:15], v[6:7], v[24:25], v[14:15] op_sel_hi:[1,0,1] neg_lo:[0,0,1] neg_hi:[0,0,1]
	v_pk_fma_f32 v[16:17], v[8:9], v[24:25], v[16:17] op_sel_hi:[1,0,1] neg_lo:[0,0,1] neg_hi:[0,0,1]
	v_pk_fma_f32 v[18:19], v[10:11], v[24:25], v[18:19] op_sel_hi:[1,0,1] neg_lo:[0,0,1] neg_hi:[0,0,1]
	v_pk_fma_f32 v[20:21], v[12:13], v[24:25], v[20:21] op_sel_hi:[1,0,1] neg_lo:[0,0,1] neg_hi:[0,0,1]
	v_cvt_pk_bf16_f32 v132, v14, v15
	v_cvt_pk_bf16_f32 v133, v16, v17
	v_cvt_pk_bf16_f32 v134, v18, v19
	v_cvt_pk_bf16_f32 v135, v20, v21
	global_store_dwordx4 v143, v[132:135], s[8:9]
	v_add_u32_e32 v143, 0x800, v143
	v_lshlrev_b32_e32 v14, 16, v76
	v_and_b32_e32 v15, 0xffff0000, v76
	v_lshlrev_b32_e32 v16, 16, v77
	v_and_b32_e32 v17, 0xffff0000, v77
	v_lshlrev_b32_e32 v18, 16, v78
	v_and_b32_e32 v19, 0xffff0000, v78
	v_lshlrev_b32_e32 v20, 16, v79
	v_and_b32_e32 v21, 0xffff0000, v79
	v_pk_add_f32 v[6:7], v[6:7], v[14:15]
	v_pk_add_f32 v[8:9], v[8:9], v[16:17]
	v_pk_add_f32 v[10:11], v[10:11], v[18:19]
	v_pk_add_f32 v[12:13], v[12:13], v[20:21]
	v_lshlrev_b32_e32 v14, 16, v108
	v_and_b32_e32 v15, 0xffff0000, v108
	v_lshlrev_b32_e32 v16, 16, v109
	v_and_b32_e32 v17, 0xffff0000, v109
	v_lshlrev_b32_e32 v18, 16, v110
	v_and_b32_e32 v19, 0xffff0000, v110
	v_lshlrev_b32_e32 v20, 16, v111
	v_and_b32_e32 v21, 0xffff0000, v111
	v_pk_add_f32 v[6:7], v[6:7], v[14:15] neg_lo:[0,1] neg_hi:[0,1]
	v_pk_add_f32 v[8:9], v[8:9], v[16:17] neg_lo:[0,1] neg_hi:[0,1]
	v_pk_add_f32 v[10:11], v[10:11], v[18:19] neg_lo:[0,1] neg_hi:[0,1]
	v_pk_add_f32 v[12:13], v[12:13], v[20:21] neg_lo:[0,1] neg_hi:[0,1]
	s_waitcnt vmcnt(19)
	v_lshlrev_b32_e32 v14, 16, v48
	v_and_b32_e32 v15, 0xffff0000, v48
	v_lshlrev_b32_e32 v16, 16, v49
	v_and_b32_e32 v17, 0xffff0000, v49
	v_lshlrev_b32_e32 v18, 16, v50
	v_and_b32_e32 v19, 0xffff0000, v50
	v_lshlrev_b32_e32 v20, 16, v51
	v_and_b32_e32 v21, 0xffff0000, v51
	v_pk_fma_f32 v[14:15], v[6:7], v[24:25], v[14:15] op_sel_hi:[1,0,1] neg_lo:[0,0,1] neg_hi:[0,0,1]
	v_pk_fma_f32 v[16:17], v[8:9], v[24:25], v[16:17] op_sel_hi:[1,0,1] neg_lo:[0,0,1] neg_hi:[0,0,1]
	v_pk_fma_f32 v[18:19], v[10:11], v[24:25], v[18:19] op_sel_hi:[1,0,1] neg_lo:[0,0,1] neg_hi:[0,0,1]
	v_pk_fma_f32 v[20:21], v[12:13], v[24:25], v[20:21] op_sel_hi:[1,0,1] neg_lo:[0,0,1] neg_hi:[0,0,1]
	v_cvt_pk_bf16_f32 v136, v14, v15
	v_cvt_pk_bf16_f32 v137, v16, v17
	v_cvt_pk_bf16_f32 v138, v18, v19
	v_cvt_pk_bf16_f32 v139, v20, v21
	global_store_dwordx4 v143, v[136:139], s[8:9]
	v_add_u32_e32 v143, 0x800, v143
	v_lshlrev_b32_e32 v14, 16, v80
	v_and_b32_e32 v15, 0xffff0000, v80
	v_lshlrev_b32_e32 v16, 16, v81
	v_and_b32_e32 v17, 0xffff0000, v81
	v_lshlrev_b32_e32 v18, 16, v82
	v_and_b32_e32 v19, 0xffff0000, v82
	v_lshlrev_b32_e32 v20, 16, v83
	v_and_b32_e32 v21, 0xffff0000, v83
	v_pk_add_f32 v[6:7], v[6:7], v[14:15]
	v_pk_add_f32 v[8:9], v[8:9], v[16:17]
	v_pk_add_f32 v[10:11], v[10:11], v[18:19]
	v_pk_add_f32 v[12:13], v[12:13], v[20:21]
	v_lshlrev_b32_e32 v14, 16, v112
	v_and_b32_e32 v15, 0xffff0000, v112
	v_lshlrev_b32_e32 v16, 16, v113
	v_and_b32_e32 v17, 0xffff0000, v113
	v_lshlrev_b32_e32 v18, 16, v114
	v_and_b32_e32 v19, 0xffff0000, v114
	v_lshlrev_b32_e32 v20, 16, v115
	v_and_b32_e32 v21, 0xffff0000, v115
	v_pk_add_f32 v[6:7], v[6:7], v[14:15] neg_lo:[0,1] neg_hi:[0,1]
	v_pk_add_f32 v[8:9], v[8:9], v[16:17] neg_lo:[0,1] neg_hi:[0,1]
	v_pk_add_f32 v[10:11], v[10:11], v[18:19] neg_lo:[0,1] neg_hi:[0,1]
	v_pk_add_f32 v[12:13], v[12:13], v[20:21] neg_lo:[0,1] neg_hi:[0,1]
	s_waitcnt vmcnt(16)
	v_lshlrev_b32_e32 v14, 16, v52
	v_and_b32_e32 v15, 0xffff0000, v52
	v_lshlrev_b32_e32 v16, 16, v53
	v_and_b32_e32 v17, 0xffff0000, v53
	v_lshlrev_b32_e32 v18, 16, v54
	v_and_b32_e32 v19, 0xffff0000, v54
	v_lshlrev_b32_e32 v20, 16, v55
	v_and_b32_e32 v21, 0xffff0000, v55
	v_pk_fma_f32 v[14:15], v[6:7], v[24:25], v[14:15] op_sel_hi:[1,0,1] neg_lo:[0,0,1] neg_hi:[0,0,1]
	v_pk_fma_f32 v[16:17], v[8:9], v[24:25], v[16:17] op_sel_hi:[1,0,1] neg_lo:[0,0,1] neg_hi:[0,0,1]
	v_pk_fma_f32 v[18:19], v[10:11], v[24:25], v[18:19] op_sel_hi:[1,0,1] neg_lo:[0,0,1] neg_hi:[0,0,1]
	v_pk_fma_f32 v[20:21], v[12:13], v[24:25], v[20:21] op_sel_hi:[1,0,1] neg_lo:[0,0,1] neg_hi:[0,0,1]
	v_cvt_pk_bf16_f32 v132, v14, v15
	v_cvt_pk_bf16_f32 v133, v16, v17
	v_cvt_pk_bf16_f32 v134, v18, v19
	v_cvt_pk_bf16_f32 v135, v20, v21
	global_store_dwordx4 v143, v[132:135], s[8:9]
	v_add_u32_e32 v143, 0x800, v143
	v_lshlrev_b32_e32 v14, 16, v84
	v_and_b32_e32 v15, 0xffff0000, v84
	v_lshlrev_b32_e32 v16, 16, v85
	v_and_b32_e32 v17, 0xffff0000, v85
	v_lshlrev_b32_e32 v18, 16, v86
	v_and_b32_e32 v19, 0xffff0000, v86
	v_lshlrev_b32_e32 v20, 16, v87
	v_and_b32_e32 v21, 0xffff0000, v87
	v_pk_add_f32 v[6:7], v[6:7], v[14:15]
	v_pk_add_f32 v[8:9], v[8:9], v[16:17]
	v_pk_add_f32 v[10:11], v[10:11], v[18:19]
	v_pk_add_f32 v[12:13], v[12:13], v[20:21]
	v_lshlrev_b32_e32 v14, 16, v116
	v_and_b32_e32 v15, 0xffff0000, v116
	v_lshlrev_b32_e32 v16, 16, v117
	v_and_b32_e32 v17, 0xffff0000, v117
	v_lshlrev_b32_e32 v18, 16, v118
	v_and_b32_e32 v19, 0xffff0000, v118
	v_lshlrev_b32_e32 v20, 16, v119
	v_and_b32_e32 v21, 0xffff0000, v119
	v_pk_add_f32 v[6:7], v[6:7], v[14:15] neg_lo:[0,1] neg_hi:[0,1]
	v_pk_add_f32 v[8:9], v[8:9], v[16:17] neg_lo:[0,1] neg_hi:[0,1]
	v_pk_add_f32 v[10:11], v[10:11], v[18:19] neg_lo:[0,1] neg_hi:[0,1]
	v_pk_add_f32 v[12:13], v[12:13], v[20:21] neg_lo:[0,1] neg_hi:[0,1]
	s_waitcnt vmcnt(13)
; __device__ __forceinline__ void unpack8(const u32x4 v, float* a) { a[0] = bflo(v.x); a[1] = bfhi(v.x); a[2] = bflo(v.y); a[3] = bfhi(v.y); a[4] = bflo(v.z); a[5] = bfhi(v.z); a[6] = bflo(v.w); a[7] = bfhi(v.w); }
; __device__ __forceinline__ void pool_block(const bf16_t* Z, bf16_t* A2, int row0, int lane) {
;     int sb, S; if (row0 < 8192) { sb = 0; S = 8192; } else if (row0 < 16384) { sb = 8192; S = 8192; } else { sb = 16384; S = 16384; }
;     const int t0 = row0 - sb, g = lane >> 4, hw = 1 << g;
;     const bf16_t* base = Z + (size_t)sb * NZ + 1536 + lane * 8;
;     ...
;     for (int i = 0; i < 16; ++i) { const int t = t0 + i;
;         int lo = t - hw; if (lo < 0) lo = 0; int hi2 = t + hw - 1; if (hi2 > S - 1) hi2 = S - 1;
;         const float inv = 1.0f / (float)(hi2 - lo + 1);
;         float self[8]; unpack8(*(const u32x4*)(base + (size_t)t * NZ), self);
;         u32x4 o; o.x = pk2(sum[0] * inv - self[0], sum[1] * inv - self[1]); o.y = pk2(sum[2] * inv - self[2], sum[3] * inv - self[3]);
;         o.z = pk2(sum[4] * inv - self[4], sum[5] * inv - self[5]); o.w = pk2(sum[6] * inv - self[6], sum[7] * inv - self[7]);
;         *(u32x4*)(A2 + (size_t)(sb + t) * DM + 512 + lane * 8) = o;
;         const int radd = t + hw, rsub = t - hw;
;         if (radd < S) { unpack8(*(const u32x4*)(base + (size_t)radd * NZ), tmp);
; #pragma unroll
;             for (int e = 0; e < 8; ++e) sum[e] += tmp[e]; }
;         if (rsub >= 0) { unpack8(*(const u32x4*)(base + (size_t)rsub * NZ), tmp);
; #pragma unroll
;             for (int e = 0; e < 8; ++e) sum[e] -= tmp[e]; }
;     }
	v_lshlrev_b32_e32 v14, 16, v56
	v_and_b32_e32 v15, 0xffff0000, v56
	v_lshlrev_b32_e32 v16, 16, v57
	v_and_b32_e32 v17, 0xffff0000, v57
	v_lshlrev_b32_e32 v18, 16, v58
	v_and_b32_e32 v19, 0xffff0000, v58
	v_lshlrev_b32_e32 v20, 16, v59
	v_and_b32_e32 v21, 0xffff0000, v59
	v_pk_fma_f32 v[14:15], v[6:7], v[24:25], v[14:15] op_sel_hi:[1,0,1] neg_lo:[0,0,1] neg_hi:[0,0,1]
	v_pk_fma_f32 v[16:17], v[8:9], v[24:25], v[16:17] op_sel_hi:[1,0,1] neg_lo:[0,0,1] neg_hi:[0,0,1]
	v_pk_fma_f32 v[18:19], v[10:11], v[24:25], v[18:19] op_sel_hi:[1,0,1] neg_lo:[0,0,1] neg_hi:[0,0,1]
	v_pk_fma_f32 v[20:21], v[12:13], v[24:25], v[20:21] op_sel_hi:[1,0,1] neg_lo:[0,0,1] neg_hi:[0,0,1]
	v_cvt_pk_bf16_f32 v136, v14, v15
	v_cvt_pk_bf16_f32 v137, v16, v17
	v_cvt_pk_bf16_f32 v138, v18, v19
	v_cvt_pk_bf16_f32 v139, v20, v21
	global_store_dwordx4 v143, v[136:139], s[8:9]
	v_add_u32_e32 v143, 0x800, v143
	v_lshlrev_b32_e32 v14, 16, v88
	v_and_b32_e32 v15, 0xffff0000, v88
	v_lshlrev_b32_e32 v16, 16, v89
	v_and_b32_e32 v17, 0xffff0000, v89
	v_lshlrev_b32_e32 v18, 16, v90
	v_and_b32_e32 v19, 0xffff0000, v90
	v_lshlrev_b32_e32 v20, 16, v91
	v_and_b32_e32 v21, 0xffff0000, v91
	v_pk_add_f32 v[6:7], v[6:7], v[14:15]
	v_pk_add_f32 v[8:9], v[8:9], v[16:17]
	v_pk_add_f32 v[10:11], v[10:11], v[18:19]
	v_pk_add_f32 v[12:13], v[12:13], v[20:21]
	v_lshlrev_b32_e32 v14, 16, v120
	v_and_b32_e32 v15, 0xffff0000, v120
	v_lshlrev_b32_e32 v16, 16, v121
	v_and_b32_e32 v17, 0xffff0000, v121
	v_lshlrev_b32_e32 v18, 16, v122
	v_and_b32_e32 v19, 0xffff0000, v122
	v_lshlrev_b32_e32 v20, 16, v123
	v_and_b32_e32 v21, 0xffff0000, v123
	v_pk_add_f32 v[6:7], v[6:7], v[14:15] neg_lo:[0,1] neg_hi:[0,1]
	v_pk_add_f32 v[8:9], v[8:9], v[16:17] neg_lo:[0,1] neg_hi:[0,1]
	v_pk_add_f32 v[10:11], v[10:11], v[18:19] neg_lo:[0,1] neg_hi:[0,1]
	v_pk_add_f32 v[12:13], v[12:13], v[20:21] neg_lo:[0,1] neg_hi:[0,1]
	s_waitcnt vmcnt(10)
	v_lshlrev_b32_e32 v14, 16, v60
	v_and_b32_e32 v15, 0xffff0000, v60
	v_lshlrev_b32_e32 v16, 16, v61
	v_and_b32_e32 v17, 0xffff0000, v61
	v_lshlrev_b32_e32 v18, 16, v62
	v_and_b32_e32 v19, 0xffff0000, v62
	v_lshlrev_b32_e32 v20, 16, v63
	v_and_b32_e32 v21, 0xffff0000, v63
	v_pk_fma_f32 v[14:15], v[6:7], v[24:25], v[14:15] op_sel_hi:[1,0,1] neg_lo:[0,0,1] neg_hi:[0,0,1]
	v_pk_fma_f32 v[16:17], v[8:9], v[24:25], v[16:17] op_sel_hi:[1,0,1] neg_lo:[0,0,1] neg_hi:[0,0,1]
	v_pk_fma_f32 v[18:19], v[10:11], v[24:25], v[18:19] op_sel_hi:[1,0,1] neg_lo:[0,0,1] neg_hi:[0,0,1]
	v_pk_fma_f32 v[20:21], v[12:13], v[24:25], v[20:21] op_sel_hi:[1,0,1] neg_lo:[0,0,1] neg_hi:[0,0,1]
	v_cvt_pk_bf16_f32 v132, v14, v15
	v_cvt_pk_bf16_f32 v133, v16, v17
	v_cvt_pk_bf16_f32 v134, v18, v19
	v_cvt_pk_bf16_f32 v135, v20, v21
	global_store_dwordx4 v143, v[132:135], s[8:9]
	v_add_u32_e32 v143, 0x800, v143
	v_lshlrev_b32_e32 v14, 16, v92
	v_and_b32_e32 v15, 0xffff0000, v92
	v_lshlrev_b32_e32 v16, 16, v93
	v_and_b32_e32 v17, 0xffff0000, v93
	v_lshlrev_b32_e32 v18, 16, v94
	v_and_b32_e32 v19, 0xffff0000, v94
	v_lshlrev_b32_e32 v20, 16, v95
	v_and_b32_e32 v21, 0xffff0000, v95
	v_pk_add_f32 v[6:7], v[6:7], v[14:15]
	v_pk_add_f32 v[8:9], v[8:9], v[16:17]
	v_pk_add_f32 v[10:11], v[10:11], v[18:19]
	v_pk_add_f32 v[12:13], v[12:13], v[20:21]
	v_lshlrev_b32_e32 v14, 16, v124
	v_and_b32_e32 v15, 0xffff0000, v124
	v_lshlrev_b32_e32 v16, 16, v125
	v_and_b32_e32 v17, 0xffff0000, v125
	v_lshlrev_b32_e32 v18, 16, v126
	v_and_b32_e32 v19, 0xffff0000, v126
	v_lshlrev_b32_e32 v20, 16, v127
	v_and_b32_e32 v21, 0xffff0000, v127
	v_pk_add_f32 v[6:7], v[6:7], v[14:15] neg_lo:[0,1] neg_hi:[0,1]
	v_pk_add_f32 v[8:9], v[8:9], v[16:17] neg_lo:[0,1] neg_hi:[0,1]
	v_pk_add_f32 v[10:11], v[10:11], v[18:19] neg_lo:[0,1] neg_hi:[0,1]
	v_pk_add_f32 v[12:13], v[12:13], v[20:21] neg_lo:[0,1] neg_hi:[0,1]
	s_waitcnt vmcnt(7)
	v_lshlrev_b32_e32 v14, 16, v64
	v_and_b32_e32 v15, 0xffff0000, v64
	v_lshlrev_b32_e32 v16, 16, v65
	v_and_b32_e32 v17, 0xffff0000, v65
	v_lshlrev_b32_e32 v18, 16, v66
	v_and_b32_e32 v19, 0xffff0000, v66
	v_lshlrev_b32_e32 v20, 16, v67
	v_and_b32_e32 v21, 0xffff0000, v67
	v_pk_fma_f32 v[14:15], v[6:7], v[24:25], v[14:15] op_sel_hi:[1,0,1] neg_lo:[0,0,1] neg_hi:[0,0,1]
	v_pk_fma_f32 v[16:17], v[8:9], v[24:25], v[16:17] op_sel_hi:[1,0,1] neg_lo:[0,0,1] neg_hi:[0,0,1]
	v_pk_fma_f32 v[18:19], v[10:11], v[24:25], v[18:19] op_sel_hi:[1,0,1] neg_lo:[0,0,1] neg_hi:[0,0,1]
	v_pk_fma_f32 v[20:21], v[12:13], v[24:25], v[20:21] op_sel_hi:[1,0,1] neg_lo:[0,0,1] neg_hi:[0,0,1]
	v_cvt_pk_bf16_f32 v136, v14, v15
	v_cvt_pk_bf16_f32 v137, v16, v17
	v_cvt_pk_bf16_f32 v138, v18, v19
	v_cvt_pk_bf16_f32 v139, v20, v21
	global_store_dwordx4 v143, v[136:139], s[8:9]
	v_add_u32_e32 v143, 0x800, v143
	v_lshlrev_b32_e32 v14, 16, v96
	v_and_b32_e32 v15, 0xffff0000, v96
	v_lshlrev_b32_e32 v16, 16, v97
	v_and_b32_e32 v17, 0xffff0000, v97
	v_lshlrev_b32_e32 v18, 16, v98
	v_and_b32_e32 v19, 0xffff0000, v98
	v_lshlrev_b32_e32 v20, 16, v99
	v_and_b32_e32 v21, 0xffff0000, v99
	v_pk_add_f32 v[6:7], v[6:7], v[14:15]
	v_pk_add_f32 v[8:9], v[8:9], v[16:17]
	v_pk_add_f32 v[10:11], v[10:11], v[18:19]
	v_pk_add_f32 v[12:13], v[12:13], v[20:21]
	v_lshlrev_b32_e32 v14, 16, v128
	v_and_b32_e32 v15, 0xffff0000, v128
	v_lshlrev_b32_e32 v16, 16, v129
	v_and_b32_e32 v17, 0xffff0000, v129
	v_lshlrev_b32_e32 v18, 16, v130
	v_and_b32_e32 v19, 0xffff0000, v130
	v_lshlrev_b32_e32 v20, 16, v131
	v_and_b32_e32 v21, 0xffff0000, v131
	v_pk_add_f32 v[6:7], v[6:7], v[14:15] neg_lo:[0,1] neg_hi:[0,1]
	v_pk_add_f32 v[8:9], v[8:9], v[16:17] neg_lo:[0,1] neg_hi:[0,1]
	v_pk_add_f32 v[10:11], v[10:11], v[18:19] neg_lo:[0,1] neg_hi:[0,1]
	v_pk_add_f32 v[12:13], v[12:13], v[20:21] neg_lo:[0,1] neg_hi:[0,1]
	s_branch .LBB0_279
.Lpool_slow:
	v_bfe_u32 v6, v2, 4, 2
	v_readlane_b32 s16, v255, 21
	v_and_b32_e32 v5, 63, v2
	v_lshlrev_b32_e64 v30, v6, 1
	v_lshl_add_u32 v31, v4, 4, s16
	v_lshlrev_b32_e32 v2, 3, v5
	v_cmp_lt_u32_e64 s[6:7], 15, v5
	v_cmp_lt_u32_e64 s[8:9], 31, v5
	v_cmp_eq_u32_e64 s[10:11], 3, v6
	v_add_u32_e32 v32, v31, v30
	v_sub_u32_e32 v33, v31, v30
	s_mov_b64 s[16:17], 0
	s_branch .LBB0_229
